# ph2 ret_kv rebalance + ph3 wave-0 offload + ph0 Kmat items to waves 4-7 (all guarded on grid 256) + 64-bit accumulator zeroing
# baseline (speedup 1.0000x reference)
; __device__ __forceinline__ void s5_build(const Frame& F, const S5P& P, bf16* W1T, bf16* WYT, float* KMAT) {
;     const int it0 = F.gw * 64 + F.lane, NT = F.NGW * 64;
;     for (int it = F.gw; it < 32 * 32; it += F.NGW) { const int g = it >> 5, j = it & 31; const float delta = expf(P.lstep[g]);
;         const float lr = P.lre[g * 64 + F.lane], li = P.lim[g * 64 + F.lane]; float pr, pi, cr, ci; cpow(lr, li, delta, (float)j, pr, pi); s5_coef(lr, li, delta, cr, ci);
.LBB0_5:
	s_or_b64 exec, exec, s[4:5]
	s_cmp_lt_i32 s80, 1
	s_cselect_b64 s[0:1], -1, 0
	s_cmp_gt_i32 s81, 0
	s_cselect_b64 s[2:3], -1, 0
	s_and_b64 s[0:1], s[0:1], s[2:3]
	s_andn2_b64 vcc, exec, s[0:1]
	v_writelane_b32 v254, s74, 3
	s_nop 1
	v_writelane_b32 v254, s75, 4
	s_cbranch_vccnz .LBB0_187
	v_mov_b32_e32 v14, v0
	s_load_dwordx2 s[28:29], s[74:75], 0xf0
	s_load_dwordx8 s[12:19], s[74:75], 0x38
	s_load_dwordx4 s[20:23], s[74:75], 0x58
	s_load_dwordx2 s[4:5], s[74:75], 0x70
	v_readfirstlane_b32 s0, v14
	s_ashr_i32 s39, s0, 6
	s_mul_i32 s38, s39, s82
	v_and_b32_e32 v34, 63, v14
	s_add_i32 s40, s38, s96
	s_mov_b32 s30, s40
	s_cmp_eq_u32 s82, 0x100
	s_cbranch_scc0 .Lmy_e2orig
	s_sub_i32 s30, s40, 0x400
.Lmy_e2orig:
	s_cmp_gt_u32 s30, 0x3ff
	v_lshrrev_b32_e32 v35, 2, v34
	v_lshlrev_b32_e32 v36, 4, v34
	s_cbranch_scc1 .LBB0_11
	v_mbcnt_lo_u32_b32 v1, -1, 0
	v_and_b32_e32 v16, 48, v36
	v_mov_b32_e32 v17, 0
	v_mbcnt_hi_u32_b32 v4, -1, v1
	s_waitcnt lgkmcnt(0)
	v_lshl_add_u64 v[2:3], s[28:29], 0, v[16:17]
	s_mov_b64 s[2:3], 0x200000
	v_lshl_add_u64 v[18:19], v[2:3], 0, s[2:3]
	v_lshlrev_b32_e32 v2, 2, v4
	v_and_b32_e32 v20, 0x100, v2
	v_and_b32_e32 v2, 3, v14
	v_mov_b32_e32 v3, 0x100
	v_lshl_or_b32 v16, v2, 4, v3
	s_mov_b32 s8, 0x6dc9c883
	s_lshl_b32 s0, s82, 3
	v_lshlrev_b32_e32 v1, 6, v35
	v_lshl_add_u64 v[22:23], s[16:17], 0, v[16:17]
	v_lshl_add_u64 v[24:25], s[18:19], 0, v[16:17]
	s_mov_b32 s1, 0x3fb8aa3b
	s_mov_b32 s2, 0xc2ce8ed0
	s_mov_b32 s3, 0x42b17218
	v_mov_b32_e32 v15, 0x7f800000
	s_mov_b32 s9, 0x3fc45f30
	s_mov_b64 s[10:11], 0x200

; __device__ __forceinline__ float ret_log2g(int h) { return log1pf(-exp2f(-5.f - (float)h)) * 1.4426950408889634f; }
; __device__ __forceinline__ void ret_kv_phase(const Frame& F, const bf16* P0, float* KV) {
;     ...
;     int u = F.bx; if (u < 2048) KV_PREFETCH(u);
;     for (; u < 2048; u += F.G) { const int h = (u >> 5) & 7; const float lg = ret_log2g(h);
.LBB0_287:
	s_mov_b32 s99, s96
	s_mov_b32 s100, s82
	s_movk_i32 s98, 0x800
	s_cmp_lg_u32 s82, 0x100
	s_cbranch_scc1 .Lmy_kvG
	s_and_b32 s98, s96, 7
	s_lshr_b32 s101, s96, 3
	s_cmp_lt_u32 s98, 4
	s_cbranch_scc0 .Lmy_kvB
	s_lshl_b32 s98, s98, 5
	s_add_i32 s96, s98, s101
	s_movk_i32 s98, 0x200
	s_branch .Lmy_kvJ

; #define LAS __attribute__((address_space(3)))
; __device__ __forceinline__ float ret_log2g(int h) { return log1pf(-exp2f(-5.f - (float)h)) * 1.4426950408889634f; }
; __device__ __forceinline__ void ret_kv_phase(const Frame& F, const bf16* P0, float* KV) {
;     LAS bf16* Vt = (LAS bf16*)F.lds; LAS bf16* Kt = Vt + 64 * VT_LD;
;     const int fr = F.lane & 15, fq = F.lane >> 4; const int s = F.tid >> 2, part = F.tid & 3;
;     v4u pv0, pv1, pk0, pk1;
;     ...
;     int u = F.bx; if (u < 2048) KV_PREFETCH(u);
;     for (; u < 2048; u += F.G) { const int h = (u >> 5) & 7; const float lg = ret_log2g(h);
.Lmy_kvG:
	v_mov_b32_e32 v20, v0
	s_cmp_ge_i32 s96, s98
	v_readfirstlane_b32 s0, v20
	s_cbranch_scc1 .LBB0_292
	s_add_u32 s4, s78, 0x13c00000
	s_addc_u32 s5, s79, 0
	s_lshl_b32 s1, s96, 4
	s_lshl_b32 s2, s96, 7
	s_and_b32 s1, s1, 0xfffff000
	s_and_b32 s2, s2, 0xf80
	v_ashrrev_i32_e32 v1, 2, v20
	s_or_b32 s1, s1, s2
	v_add_u32_e32 v2, s1, v1
	v_ashrrev_i32_e32 v3, 31, v2
	v_lshlrev_b64 v[2:3], 12, v[2:3]
	s_lshl_b32 s1, s96, 2
	v_and_b32_e32 v21, 3, v20
	v_lshl_add_u64 v[2:3], s[4:5], 0, v[2:3]
	s_and_b32 s6, s1, 0x380
	s_mov_b32 s7, 0
	v_lshl_add_u64 v[2:3], v[2:3], 0, s[6:7]
	v_mov_b32_e32 v19, 0
	v_lshlrev_b32_e32 v18, 5, v21
	v_lshl_add_u64 v[22:23], v[2:3], 0, v[18:19]
	global_load_dwordx4 v[2:5], v[22:23], off offset:2048
	global_load_dwordx4 v[6:9], v[22:23], off offset:2064
	global_load_dwordx4 v[10:13], v[22:23], off offset:1040
	global_load_dwordx4 v[14:17], v[22:23], off offset:1024
	v_and_b32_e32 v26, 15, v20
	v_bfe_u32 v20, v20, 4, 2
	s_ashr_i32 s1, s0, 7
	v_lshl_add_u32 v28, v20, 4, 0
	v_lshlrev_b32_e32 v24, 8, v20
	v_lshl_or_b32 v20, s1, 4, v26
	s_movk_i32 s2, 0x110
	v_lshlrev_b32_e32 v18, 4, v21
	v_mul_u32_u24_e32 v21, 0x880, v21
	v_mul_lo_u32 v27, v20, s2
	s_lshr_b32 s2, s0, 1
	s_ashr_i32 s97, s96, 31
	s_lshl_b32 s0, s0, 1
	v_lshlrev_b32_e32 v22, 1, v1
	v_lshlrev_b32_e32 v21, 1, v21
	v_and_or_b32 v20, s2, 32, v26
	s_lshl_b64 s[2:3], s[96:97], 14
	s_and_b32 s0, s0, 0x80
	v_add3_u32 v22, 0, v22, v21
	v_sub_u32_e32 v21, 0x7f, v1
	v_mul_u32_u24_e32 v29, 0x110, v20
	v_or_b32_e32 v20, 16, v20
	s_or_b32 s0, s2, s0
	v_lshl_or_b32 v24, s1, 10, v24
	v_cvt_f32_i32_e32 v23, v21
	v_mul_u32_u24_e32 v30, 0x110, v20
	v_mov_b32_e32 v20, s0
	v_mov_b32_e32 v21, s3
	v_ashrrev_i32_e32 v25, 31, v24
	v_lshl_add_u64 v[20:21], v[24:25], 2, v[20:21]
	v_lshl_or_b32 v20, v26, 2, v20
	v_lshl_add_u64 v[20:21], s[78:79], 0, v[20:21]
	s_mov_b64 s[0:1], 0xbc00200
	v_lshl_add_u64 v[20:21], v[20:21], 0, s[0:1]
	s_ashr_i32 s1, s82, 31
	s_mov_b32 s0, s82
	s_add_i32 s6, s96, s82
	s_lshl_b64 s[8:9], s[0:1], 14
	s_lshl_b32 s0, s6, 1
	s_lshl_b32 s1, s82, 1
	s_lshl_b32 s2, s6, 7
	s_lshl_b32 s3, s82, 7
	s_lshl_b32 s12, s6, 4
	s_lshl_b32 s13, s82, 4
	s_mov_b32 s14, 0xc2fc0000
	v_mov_b32_e32 v24, 0x42800000
	s_mov_b32 s15, 0x3f2aaaab
	v_mov_b32_e32 v25, 0x3ecc95a3
	s_mov_b32 s16, 0x3f317218
	s_mov_b32 s17, 0x33800000
	s_movk_i32 s18, 0x7fff
	v_lshlrev_b32_e32 v18, 1, v18
	v_add_u32_e32 v26, v28, v27
	v_add_u32_e32 v27, v28, v29
	v_add_u32_e32 v28, v28, v30
	v_mov_b32_e32 v29, 0x7fc00000
	v_mov_b32_e32 v30, 0xff800000
	v_not_b32_e32 v31, 63
	s_mov_b32 s19, s96
	s_branch .LBB0_290
